# mirror: static s_setprio 1 for waves 0-3 (older half) in the sparse-attention item loop
# speedup vs baseline: 1.0157x; 1.0157x over previous
; __device__ __forceinline__ void attn_item(const Ptrs& P, unsigned char* lds, int b, int tq0, int tid) {
;     const int lane = tid & 63, w = __builtin_amdgcn_readfirstlane(tid >> 6), g = lane >> 4, r16 = lane & 15;
;     constexpr int SP = 264;
;     bf16_t* stg = (bf16_t*)lds;
;     unsigned char* l2 = lds + 135168;
;     unsigned short* sel = (unsigned short*)l2;
;     unsigned* cntw = (unsigned*)(l2 + 2048);
;     unsigned* gte = (unsigned*)(l2 + 2048 + 256);
;     bf16_t* Pm = (bf16_t*)(l2 + 4096);
;     const size_t rowb = (size_t)b * T;
;     const int tmax = tq0 + 3;
;     if (tmax < 256 || (DBG & 4)) {
; __global__ void __launch_bounds__(512, 2) mega_fwd(Args args) {
;     ...
;                 if (tid == 0) *(volatile int*)(lds + 147712) = (int)atomicAdd(ctl + 64 * b, 1u);
;                 __syncthreads();
;                 const int item = *(volatile int*)(lds + 147712);
;                 if (item >= T / 4) break;
;                 attn_item(P, lds, b, 4 * ((T / 4 - 1) - item), tid);
.Lq_have_item:
	s_movk_i32 s12, 0x800
	s_waitcnt lgkmcnt(0)
	v_cmp_gt_i32_e32 vcc, s12, v0
	s_mov_b64 s[12:13], -1
	s_and_saveexec_b64 s[70:71], vcc
	s_cbranch_execz .LBB0_465
	s_and_saveexec_b64 s[90:91], s[0:1]
	v_mov_b32_e32 v255, 1
	global_atomic_add v254, v165, v255, s[46:47] sc0
	s_mov_b64 exec, s[90:91]
	s_nop 0
	s_nop 0
	s_nop 0
	s_nop 0
	s_nop 0
	s_nop 0
	s_nop 0
	s_nop 0
	v_lshlrev_b32_e32 v64, 2, v0
	v_sub_u32_e32 v124, 0x1ffc, v64
	v_readfirstlane_b32 s63, v188
	s_movk_i32 s12, 0xfc
	s_lshr_b32 s62, s63, 6
	s_cmp_gt_u32 s62, 3
	s_cbranch_scc1 .Lprio_skip
	s_setprio 1
